# v037 + FFN-up SwiGLU epilogue: row store addresses derived from the first row by one 64-bit add (drops v_mad_i64 + 2 adds per row)
# speedup vs baseline: 1.0052x; 1.0052x over previous
; #define LAS __attribute__((address_space(3)))
; __device__ __forceinline__ float siluf_(float x) { return x * __builtin_amdgcn_rcpf(1.f + __expf(-x)); }
; __device__ __forceinline__ u32x4 pack8(const float* f) { u32x4 o; o.x = pk2(f[0], f[1]); o.y = pk2(f[2], f[3]); o.z = pk2(f[4], f[5]); o.w = pk2(f[6], f[7]); return o; }
;     __device__ __forceinline__ void operator()(const Acc& acc, const Unit& u, int wr, int wc, int fr, int fq, LAS const float* rtab) const {
;         const int row0 = u.pm * BM + wr * 64 + fr;
;         float rsv[8];
; #pragma unroll
;         for (int i = 0; i < 8; ++i) rsv[i] = rtab[wr * 64 + fr + (i >> 2) * HALF + (i & 3) * 16];
; #pragma unroll
;         for (int ai = 0; ai < 2; ++ai)
; #pragma unroll
;             for (int m = 0; m < 4; ++m) {
;                 const int row = row0 + ai * HALF + m * 16;
;                 const float rs = rsv[ai * 4 + m];
;                 float h[8];
; #pragma unroll
;                 for (int n = 0; n < 2; ++n)
; #pragma unroll
;                     for (int j = 0; j < 4; ++j) { const float gg = acc[ai][0][m][n][j] * rs, uu = acc[ai][1][m][n][j] * rs; h[n * 4 + j] = siluf_(gg) * uu; }
;                 *(u32x4*)(H + (size_t)row * FF + u.pn * 128 + wc * 32 + 8 * fq) = pack8(h);
;             }
.LBB0_3855:
	ds_read2_b32 v[152:153], v156 offset1:16
	ds_read2_b32 v[150:151], v156 offset0:32 offset1:48
	ds_read2_b32 v[148:149], v156 offset0:128 offset1:144
	s_waitcnt lgkmcnt(0)
	ds_read2_b32 v[146:147], v156 offset0:160 offset1:176
	s_lshl_b32 s8, s26, 7
	v_pk_mul_f32 v[126:127], v[126:127], v[152:153] op_sel_hi:[1,0]
	v_pk_mul_f32 v[122:123], v[122:123], v[152:153] op_sel_hi:[1,0]
	v_mul_f32_e32 v145, 0xbfb8aa3b, v126
	v_exp_f32_e32 v145, v145
	v_pk_mul_f32 v[124:125], v[124:125], v[152:153] op_sel_hi:[1,0]
	v_pk_mul_f32 v[118:119], v[118:119], v[152:153] op_sel_hi:[1,0]
	v_pk_mul_f32 v[114:115], v[114:115], v[152:153] op_sel_hi:[1,0]
	v_add_f32_e32 v145, 1.0, v145
	v_rcp_f32_e32 v174, v145
	v_mul_f32_e32 v145, 0xbfb8aa3b, v127
	v_exp_f32_e32 v145, v145
	v_pk_mul_f32 v[116:117], v[116:117], v[152:153] op_sel_hi:[1,0]
	v_add_u32_e32 v173, s10, v65
	s_ashr_i32 s9, s8, 31
	v_add_f32_e32 v145, 1.0, v145
	v_rcp_f32_e32 v175, v145
	s_movk_i32 s26, 0x1600
	s_lshl_b64 s[8:9], s[8:9], 1
	v_mov_b32_e32 v145, v64
	v_pk_mul_f32 v[126:127], v[126:127], v[174:175]
	v_pk_mul_f32 v[94:95], v[94:95], v[150:151] op_sel_hi:[1,0]
	v_pk_mul_f32 v[122:123], v[122:123], v[126:127]
	v_pk_mul_f32 v[126:127], v[128:129], v[152:153] op_sel_hi:[1,0]
	v_pk_mul_f32 v[90:91], v[90:91], v[150:151] op_sel_hi:[1,0]
	v_mul_f32_e32 v128, 0xbfb8aa3b, v126
	v_mul_f32_e32 v129, 0xbfb8aa3b, v127
	v_exp_f32_e32 v128, v128
	v_exp_f32_e32 v129, v129
	v_pk_mul_f32 v[92:93], v[92:93], v[150:151] op_sel_hi:[1,0]
	v_pk_mul_f32 v[86:87], v[86:87], v[150:151] op_sel_hi:[1,0]
	v_add_f32_e32 v128, 1.0, v128
	v_add_f32_e32 v129, 1.0, v129
	v_rcp_f32_e32 v128, v128
	v_rcp_f32_e32 v129, v129
	v_pk_mul_f32 v[82:83], v[82:83], v[150:151] op_sel_hi:[1,0]
	v_pk_mul_f32 v[84:85], v[84:85], v[150:151] op_sel_hi:[1,0]
	v_pk_mul_f32 v[60:61], v[60:61], v[148:149] op_sel_hi:[1,0]
	v_pk_mul_f32 v[126:127], v[126:127], v[128:129]
	v_pk_mul_f32 v[56:57], v[56:57], v[148:149] op_sel_hi:[1,0]
	v_pk_mul_f32 v[124:125], v[124:125], v[126:127]
	v_mul_f32_e32 v126, 0xbfb8aa3b, v118
	v_mul_f32_e32 v127, 0xbfb8aa3b, v119
	v_exp_f32_e32 v126, v126
	v_exp_f32_e32 v127, v127
	v_pk_mul_f32 v[58:59], v[58:59], v[148:149] op_sel_hi:[1,0]
	v_pk_mul_f32 v[52:53], v[52:53], v[148:149] op_sel_hi:[1,0]
	v_add_f32_e32 v126, 1.0, v126
	v_add_f32_e32 v127, 1.0, v127
	v_rcp_f32_e32 v126, v126
	v_rcp_f32_e32 v127, v127
	v_pk_mul_f32 v[48:49], v[48:49], v[148:149] op_sel_hi:[1,0]
	v_pk_mul_f32 v[50:51], v[50:51], v[148:149] op_sel_hi:[1,0]
	s_waitcnt lgkmcnt(0)
	v_pk_mul_f32 v[28:29], v[28:29], v[146:147] op_sel_hi:[1,0]
	v_pk_mul_f32 v[118:119], v[118:119], v[126:127]
	v_pk_mul_f32 v[24:25], v[24:25], v[146:147] op_sel_hi:[1,0]
	v_pk_mul_f32 v[114:115], v[114:115], v[118:119]
	v_pk_mul_f32 v[118:119], v[120:121], v[152:153] op_sel_hi:[1,0]
	v_pk_mul_f32 v[26:27], v[26:27], v[146:147] op_sel_hi:[1,0]
	v_mul_f32_e32 v120, 0xbfb8aa3b, v118
	v_mul_f32_e32 v121, 0xbfb8aa3b, v119
	v_exp_f32_e32 v120, v120
	v_exp_f32_e32 v121, v121
	v_pk_mul_f32 v[20:21], v[20:21], v[146:147] op_sel_hi:[1,0]
	v_pk_mul_f32 v[16:17], v[16:17], v[146:147] op_sel_hi:[1,0]
	v_add_f32_e32 v120, 1.0, v120
	v_add_f32_e32 v121, 1.0, v121
	v_rcp_f32_e32 v120, v120
	v_rcp_f32_e32 v121, v121
	v_pk_mul_f32 v[18:19], v[18:19], v[146:147] op_sel_hi:[1,0]
	s_and_b64 vcc, exec, s[38:39]
	v_pk_mul_f32 v[118:119], v[118:119], v[120:121]
	s_nop 0
	v_pk_mul_f32 v[120:121], v[116:117], v[118:119]
	v_cvt_pk_bf16_f32 v118, v114, v115
	v_mov_b64_e32 v[114:115], s[50:51]
	v_cvt_pk_bf16_f32 v119, v120, v121
	v_mad_i64_i32 v[120:121], s[10:11], v173, s26, v[114:115]
	v_lshl_add_u64 v[120:121], v[120:121], 0, s[8:9]
	v_lshl_add_u64 v[120:121], v[120:121], 0, s[80:81]
	v_cvt_pk_bf16_f32 v116, v122, v123
	v_cvt_pk_bf16_f32 v117, v124, v125
	v_lshl_add_u64 v[120:121], v[120:121], 0, v[144:145]
	v_mov_b64_e32 v[250:251], v[120:121]
	flat_store_dwordx4 v[120:121], v[116:119]
	s_nop 1
	v_mov_b32_e32 v116, v153
	v_pk_mul_f32 v[110:111], v[110:111], v[116:117] op_sel_hi:[1,0]
	s_nop 0
	v_mul_f32_e32 v117, 0xbfb8aa3b, v110
	v_exp_f32_e32 v117, v117
	s_nop 0
	v_add_f32_e32 v117, 1.0, v117
	v_rcp_f32_e32 v118, v117
	v_pk_mul_f32 v[106:107], v[106:107], v[116:117] op_sel_hi:[1,0]
	v_mul_f32_e32 v117, 0xbfb8aa3b, v111
	v_exp_f32_e32 v117, v117
	s_nop 0
	v_add_f32_e32 v117, 1.0, v117
	v_rcp_f32_e32 v119, v117
	v_pk_mul_f32 v[108:109], v[108:109], v[116:117] op_sel_hi:[1,0]
	v_pk_mul_f32 v[102:103], v[102:103], v[116:117] op_sel_hi:[1,0]
	v_pk_mul_f32 v[98:99], v[98:99], v[116:117] op_sel_hi:[1,0]
	v_pk_mul_f32 v[110:111], v[110:111], v[118:119]
	v_pk_mul_f32 v[100:101], v[100:101], v[116:117] op_sel_hi:[1,0]
	v_pk_mul_f32 v[106:107], v[106:107], v[110:111]
	v_pk_mul_f32 v[110:111], v[112:113], v[116:117] op_sel_hi:[1,0]
	s_nop 0
	v_mul_f32_e32 v112, 0xbfb8aa3b, v110
	v_mul_f32_e32 v113, 0xbfb8aa3b, v111
	v_exp_f32_e32 v112, v112
	v_exp_f32_e32 v113, v113
	v_add_f32_e32 v112, 1.0, v112
	v_add_f32_e32 v113, 1.0, v113
	v_rcp_f32_e32 v112, v112
	v_rcp_f32_e32 v113, v113
	s_nop 0
	v_pk_mul_f32 v[110:111], v[110:111], v[112:113]
	s_nop 0
	v_pk_mul_f32 v[108:109], v[108:109], v[110:111]
	v_mul_f32_e32 v110, 0xbfb8aa3b, v102
	v_mul_f32_e32 v111, 0xbfb8aa3b, v103
	v_exp_f32_e32 v110, v110
	v_exp_f32_e32 v111, v111
	v_add_f32_e32 v110, 1.0, v110
	v_add_f32_e32 v111, 1.0, v111
	v_rcp_f32_e32 v110, v110
	v_rcp_f32_e32 v111, v111
	s_nop 0
	v_pk_mul_f32 v[102:103], v[102:103], v[110:111]
	s_nop 0
	v_pk_mul_f32 v[102:103], v[98:99], v[102:103]
	v_pk_mul_f32 v[98:99], v[104:105], v[116:117] op_sel_hi:[1,0]
	v_or_b32_e32 v110, 16, v173
	v_mul_f32_e32 v104, 0xbfb8aa3b, v98
	v_mul_f32_e32 v105, 0xbfb8aa3b, v99
; __device__ __forceinline__ float siluf_(float x) { return x * __builtin_amdgcn_rcpf(1.f + __expf(-x)); }
; __device__ __forceinline__ u32x4 pack8(const float* f) { u32x4 o; o.x = pk2(f[0], f[1]); o.y = pk2(f[2], f[3]); o.z = pk2(f[4], f[5]); o.w = pk2(f[6], f[7]); return o; }
;     __device__ __forceinline__ void operator()(const Acc& acc, const Unit& u, int wr, int wc, int fr, int fq, LAS const float* rtab) const {
;     ...
;             for (int m = 0; m < 4; ++m) {
;                 const int row = row0 + ai * HALF + m * 16;
;                 const float rs = rsv[ai * 4 + m];
;                 float h[8];
; #pragma unroll
;                 for (int n = 0; n < 2; ++n)
; #pragma unroll
;                     for (int j = 0; j < 4; ++j) { const float gg = acc[ai][0][m][n][j] * rs, uu = acc[ai][1][m][n][j] * rs; h[n * 4 + j] = siluf_(gg) * uu; }
;                 *(u32x4*)(H + (size_t)row * FF + u.pn * 128 + wc * 32 + 8 * fq) = pack8(h);
	v_exp_f32_e32 v104, v104
	v_exp_f32_e32 v105, v105
	v_add_f32_e32 v104, 1.0, v104
	v_add_f32_e32 v105, 1.0, v105
	v_rcp_f32_e32 v104, v104
	v_rcp_f32_e32 v105, v105
	s_nop 0
	v_pk_mul_f32 v[98:99], v[98:99], v[104:105]
	s_nop 0
	v_pk_mul_f32 v[104:105], v[100:101], v[98:99]
	v_cvt_pk_bf16_f32 v100, v102, v103
	s_mov_b64 s[100:101], 0x16000
	v_cvt_pk_bf16_f32 v98, v106, v107
	v_cvt_pk_bf16_f32 v99, v108, v109
	v_cvt_pk_bf16_f32 v101, v104, v105
	v_lshl_add_u64 v[102:103], v[250:251], 0, s[100:101]
	flat_store_dwordx4 v[102:103], v[98:101]
	s_nop 1
	v_mul_f32_e32 v98, 0xbfb8aa3b, v94
	v_mul_f32_e32 v99, 0xbfb8aa3b, v95
	v_exp_f32_e32 v98, v98
	v_exp_f32_e32 v99, v99
	v_add_f32_e32 v98, 1.0, v98
	v_add_f32_e32 v99, 1.0, v99
	v_rcp_f32_e32 v98, v98
	v_rcp_f32_e32 v99, v99
	s_nop 0
	v_pk_mul_f32 v[94:95], v[94:95], v[98:99]
	s_nop 0
	v_pk_mul_f32 v[90:91], v[90:91], v[94:95]
	v_pk_mul_f32 v[94:95], v[96:97], v[150:151] op_sel_hi:[1,0]
	s_nop 0
	v_mul_f32_e32 v96, 0xbfb8aa3b, v94
	v_mul_f32_e32 v97, 0xbfb8aa3b, v95
	v_exp_f32_e32 v96, v96
	v_exp_f32_e32 v97, v97
	v_add_f32_e32 v96, 1.0, v96
	v_add_f32_e32 v97, 1.0, v97
	v_rcp_f32_e32 v96, v96
	v_rcp_f32_e32 v97, v97
	s_nop 0
	v_pk_mul_f32 v[94:95], v[94:95], v[96:97]
	s_nop 0
	v_pk_mul_f32 v[92:93], v[92:93], v[94:95]
	v_mul_f32_e32 v94, 0xbfb8aa3b, v86
	v_mul_f32_e32 v95, 0xbfb8aa3b, v87
	v_exp_f32_e32 v94, v94
	v_exp_f32_e32 v95, v95
	v_add_f32_e32 v94, 1.0, v94
	v_add_f32_e32 v95, 1.0, v95
	v_rcp_f32_e32 v94, v94
	v_rcp_f32_e32 v95, v95
	s_nop 0
	v_pk_mul_f32 v[86:87], v[86:87], v[94:95]
	s_nop 0
	v_pk_mul_f32 v[86:87], v[82:83], v[86:87]
	v_pk_mul_f32 v[82:83], v[88:89], v[150:151] op_sel_hi:[1,0]
	v_or_b32_e32 v94, 32, v173
	v_mul_f32_e32 v88, 0xbfb8aa3b, v82
	v_mul_f32_e32 v89, 0xbfb8aa3b, v83
	v_exp_f32_e32 v88, v88
	v_exp_f32_e32 v89, v89
	v_add_f32_e32 v88, 1.0, v88
	v_add_f32_e32 v89, 1.0, v89
	v_rcp_f32_e32 v88, v88
	v_rcp_f32_e32 v89, v89
	s_nop 0
	v_pk_mul_f32 v[82:83], v[82:83], v[88:89]
	s_nop 0
	v_pk_mul_f32 v[88:89], v[84:85], v[82:83]
	v_cvt_pk_bf16_f32 v84, v86, v87
	s_mov_b64 s[100:101], 0x2c000
	v_cvt_pk_bf16_f32 v82, v90, v91
	v_cvt_pk_bf16_f32 v83, v92, v93
	v_cvt_pk_bf16_f32 v85, v88, v89
	v_lshl_add_u64 v[86:87], v[250:251], 0, s[100:101]
	flat_store_dwordx4 v[86:87], v[82:85]
	s_nop 1
	v_mov_b32_e32 v82, v151
	v_pk_mul_f32 v[78:79], v[78:79], v[82:83] op_sel_hi:[1,0]
	s_nop 0
	v_mul_f32_e32 v83, 0xbfb8aa3b, v78
	v_exp_f32_e32 v83, v83
	s_nop 0
	v_add_f32_e32 v83, 1.0, v83
	v_rcp_f32_e32 v84, v83
	v_pk_mul_f32 v[74:75], v[74:75], v[82:83] op_sel_hi:[1,0]
	v_mul_f32_e32 v83, 0xbfb8aa3b, v79
	v_exp_f32_e32 v83, v83
	s_nop 0
	v_add_f32_e32 v83, 1.0, v83
	v_rcp_f32_e32 v85, v83
	v_pk_mul_f32 v[76:77], v[76:77], v[82:83] op_sel_hi:[1,0]
	v_pk_mul_f32 v[70:71], v[70:71], v[82:83] op_sel_hi:[1,0]
	v_pk_mul_f32 v[66:67], v[66:67], v[82:83] op_sel_hi:[1,0]
	v_pk_mul_f32 v[78:79], v[78:79], v[84:85]
	v_pk_mul_f32 v[68:69], v[68:69], v[82:83] op_sel_hi:[1,0]
	v_pk_mul_f32 v[74:75], v[74:75], v[78:79]
	v_pk_mul_f32 v[78:79], v[80:81], v[82:83] op_sel_hi:[1,0]
	s_nop 0
	v_mul_f32_e32 v80, 0xbfb8aa3b, v78
	v_mul_f32_e32 v81, 0xbfb8aa3b, v79
	v_exp_f32_e32 v80, v80
	v_exp_f32_e32 v81, v81
	v_add_f32_e32 v80, 1.0, v80
	v_add_f32_e32 v81, 1.0, v81
	v_rcp_f32_e32 v80, v80
	v_rcp_f32_e32 v81, v81
	s_nop 0
	v_pk_mul_f32 v[78:79], v[78:79], v[80:81]
	s_nop 0
	v_pk_mul_f32 v[76:77], v[76:77], v[78:79]
	v_mul_f32_e32 v78, 0xbfb8aa3b, v70
	v_mul_f32_e32 v79, 0xbfb8aa3b, v71
	v_exp_f32_e32 v78, v78
	v_exp_f32_e32 v79, v79
	v_add_f32_e32 v78, 1.0, v78
	v_add_f32_e32 v79, 1.0, v79
	v_rcp_f32_e32 v78, v78
	v_rcp_f32_e32 v79, v79
	s_nop 0
	v_pk_mul_f32 v[70:71], v[70:71], v[78:79]
	s_nop 0
	v_pk_mul_f32 v[70:71], v[66:67], v[70:71]
	v_pk_mul_f32 v[66:67], v[72:73], v[82:83] op_sel_hi:[1,0]
	v_or_b32_e32 v78, 48, v173
	v_mul_f32_e32 v72, 0xbfb8aa3b, v66
	v_mul_f32_e32 v73, 0xbfb8aa3b, v67
	v_exp_f32_e32 v72, v72
	v_exp_f32_e32 v73, v73
	v_add_f32_e32 v72, 1.0, v72
	v_add_f32_e32 v73, 1.0, v73
	v_rcp_f32_e32 v72, v72
	v_rcp_f32_e32 v73, v73
	s_nop 0
	v_pk_mul_f32 v[66:67], v[66:67], v[72:73]
	s_nop 0
	v_pk_mul_f32 v[72:73], v[68:69], v[66:67]
	v_cvt_pk_bf16_f32 v68, v70, v71
	s_mov_b64 s[100:101], 0x42000
	v_cvt_pk_bf16_f32 v66, v74, v75
	v_cvt_pk_bf16_f32 v67, v76, v77
	v_cvt_pk_bf16_f32 v69, v72, v73
	v_lshl_add_u64 v[70:71], v[250:251], 0, s[100:101]
	flat_store_dwordx4 v[70:71], v[66:69]
	s_nop 1
	v_mul_f32_e32 v66, 0xbfb8aa3b, v60
	v_mul_f32_e32 v67, 0xbfb8aa3b, v61
	v_exp_f32_e32 v66, v66
	v_exp_f32_e32 v67, v67
	v_add_u32_e32 v68, 0x80, v173
	v_add_f32_e32 v66, 1.0, v66
	v_add_f32_e32 v67, 1.0, v67
	v_rcp_f32_e32 v66, v66
	v_rcp_f32_e32 v67, v67
	s_nop 0
	v_pk_mul_f32 v[60:61], v[60:61], v[66:67]
	s_nop 0
	v_pk_mul_f32 v[56:57], v[56:57], v[60:61]
	v_pk_mul_f32 v[60:61], v[62:63], v[148:149] op_sel_hi:[1,0]
	s_nop 0
	v_mul_f32_e32 v62, 0xbfb8aa3b, v60
	v_mul_f32_e32 v63, 0xbfb8aa3b, v61
	v_exp_f32_e32 v62, v62
	v_exp_f32_e32 v63, v63
	v_add_f32_e32 v62, 1.0, v62
	v_add_f32_e32 v63, 1.0, v63
	v_rcp_f32_e32 v62, v62
	v_rcp_f32_e32 v63, v63
	s_nop 0
	v_pk_mul_f32 v[60:61], v[60:61], v[62:63]
	s_nop 0
	v_pk_mul_f32 v[58:59], v[58:59], v[60:61]
	v_mul_f32_e32 v60, 0xbfb8aa3b, v52
	v_mul_f32_e32 v61, 0xbfb8aa3b, v53
	v_exp_f32_e32 v60, v60
	v_exp_f32_e32 v61, v61
	v_add_f32_e32 v60, 1.0, v60
	v_add_f32_e32 v61, 1.0, v61
	v_rcp_f32_e32 v60, v60
	v_rcp_f32_e32 v61, v61
	s_nop 0
	v_pk_mul_f32 v[52:53], v[52:53], v[60:61]
	s_nop 0
	v_pk_mul_f32 v[52:53], v[48:49], v[52:53]
	v_pk_mul_f32 v[48:49], v[54:55], v[148:149] op_sel_hi:[1,0]
	s_nop 0
	v_mul_f32_e32 v54, 0xbfb8aa3b, v48
	v_mul_f32_e32 v55, 0xbfb8aa3b, v49
; __device__ __forceinline__ float siluf_(float x) { return x * __builtin_amdgcn_rcpf(1.f + __expf(-x)); }
; __device__ __forceinline__ u32x4 pack8(const float* f) { u32x4 o; o.x = pk2(f[0], f[1]); o.y = pk2(f[2], f[3]); o.z = pk2(f[4], f[5]); o.w = pk2(f[6], f[7]); return o; }
; #define PG8_BAR __builtin_amdgcn_s_barrier()
; template <class Epi>
; __device__ __forceinline__ void gemm_phase(LAS unsigned char* lds, const Gemm g, const StaticOrder& S, const Epi& E) {
;     ...
;         if (!has_next) break;
; #pragma unroll
;         for (int a = 0; a < 2; ++a)
; #pragma unroll
;             for (int b = 0; b < 2; ++b)
; #pragma unroll
;                 for (int m = 0; m < 4; ++m)
; #pragma unroll
;                     for (int n = 0; n < 2; ++n) acc[a][b][m][n] = (f32x4){0.f, 0.f, 0.f, 0.f};
;         cur = nxt; cA = nA; cB = nB; ++ui;
;         if (wr == 1) PG8_BAR;
;     __device__ __forceinline__ void operator()(const Acc& acc, const Unit& u, int wr, int wc, int fr, int fq, LAS const float* rtab) const {
;     ...
;         for (int ai = 0; ai < 2; ++ai)
; #pragma unroll
;             for (int m = 0; m < 4; ++m) {
;                 const int row = row0 + ai * HALF + m * 16;
;                 const float rs = rsv[ai * 4 + m];
;                 float h[8];
; #pragma unroll
;                 for (int n = 0; n < 2; ++n)
; #pragma unroll
;                     for (int j = 0; j < 4; ++j) { const float gg = acc[ai][0][m][n][j] * rs, uu = acc[ai][1][m][n][j] * rs; h[n * 4 + j] = siluf_(gg) * uu; }
;                 *(u32x4*)(H + (size_t)row * FF + u.pn * 128 + wc * 32 + 8 * fq) = pack8(h);
;             }
	v_exp_f32_e32 v54, v54
	v_exp_f32_e32 v55, v55
	v_add_f32_e32 v54, 1.0, v54
	v_add_f32_e32 v55, 1.0, v55
	v_rcp_f32_e32 v54, v54
	v_rcp_f32_e32 v55, v55
	s_nop 0
	v_pk_mul_f32 v[48:49], v[48:49], v[54:55]
	s_nop 0
	v_pk_mul_f32 v[54:55], v[50:51], v[48:49]
	v_cvt_pk_bf16_f32 v50, v52, v53
	s_mov_b64 s[100:101], 0xb0000
	v_cvt_pk_bf16_f32 v48, v56, v57
	v_cvt_pk_bf16_f32 v49, v58, v59
	v_cvt_pk_bf16_f32 v51, v54, v55
	v_lshl_add_u64 v[52:53], v[250:251], 0, s[100:101]
	flat_store_dwordx4 v[52:53], v[48:51]
	s_nop 1
	v_mov_b32_e32 v48, v149
	v_pk_mul_f32 v[44:45], v[44:45], v[48:49] op_sel_hi:[1,0]
	s_nop 0
	v_mul_f32_e32 v49, 0xbfb8aa3b, v44
	v_exp_f32_e32 v49, v49
	s_nop 0
	v_add_f32_e32 v49, 1.0, v49
	v_rcp_f32_e32 v50, v49
	v_pk_mul_f32 v[40:41], v[40:41], v[48:49] op_sel_hi:[1,0]
	v_mul_f32_e32 v49, 0xbfb8aa3b, v45
	v_exp_f32_e32 v49, v49
	s_nop 0
	v_add_f32_e32 v49, 1.0, v49
	v_rcp_f32_e32 v51, v49
	v_pk_mul_f32 v[42:43], v[42:43], v[48:49] op_sel_hi:[1,0]
	v_pk_mul_f32 v[36:37], v[36:37], v[48:49] op_sel_hi:[1,0]
	v_pk_mul_f32 v[32:33], v[32:33], v[48:49] op_sel_hi:[1,0]
	v_pk_mul_f32 v[44:45], v[44:45], v[50:51]
	v_pk_mul_f32 v[34:35], v[34:35], v[48:49] op_sel_hi:[1,0]
	v_pk_mul_f32 v[40:41], v[40:41], v[44:45]
	v_pk_mul_f32 v[44:45], v[46:47], v[48:49] op_sel_hi:[1,0]
	s_nop 0
	v_mul_f32_e32 v46, 0xbfb8aa3b, v44
	v_mul_f32_e32 v47, 0xbfb8aa3b, v45
	v_exp_f32_e32 v46, v46
	v_exp_f32_e32 v47, v47
	v_add_f32_e32 v46, 1.0, v46
	v_add_f32_e32 v47, 1.0, v47
	v_rcp_f32_e32 v46, v46
	v_rcp_f32_e32 v47, v47
	s_nop 0
	v_pk_mul_f32 v[44:45], v[44:45], v[46:47]
	s_nop 0
	v_pk_mul_f32 v[42:43], v[42:43], v[44:45]
	v_mul_f32_e32 v44, 0xbfb8aa3b, v36
	v_mul_f32_e32 v45, 0xbfb8aa3b, v37
	v_exp_f32_e32 v44, v44
	v_exp_f32_e32 v45, v45
	v_add_f32_e32 v44, 1.0, v44
	v_add_f32_e32 v45, 1.0, v45
	v_rcp_f32_e32 v44, v44
	v_rcp_f32_e32 v45, v45
	s_nop 0
	v_pk_mul_f32 v[36:37], v[36:37], v[44:45]
	s_nop 0
	v_pk_mul_f32 v[36:37], v[32:33], v[36:37]
	v_pk_mul_f32 v[32:33], v[38:39], v[48:49] op_sel_hi:[1,0]
	v_add_u32_e32 v44, 0x90, v173
	v_mul_f32_e32 v38, 0xbfb8aa3b, v32
	v_mul_f32_e32 v39, 0xbfb8aa3b, v33
	v_exp_f32_e32 v38, v38
	v_exp_f32_e32 v39, v39
	v_add_f32_e32 v38, 1.0, v38
	v_add_f32_e32 v39, 1.0, v39
	v_rcp_f32_e32 v38, v38
	v_rcp_f32_e32 v39, v39
	s_nop 0
	v_pk_mul_f32 v[32:33], v[32:33], v[38:39]
	s_nop 0
	v_pk_mul_f32 v[38:39], v[34:35], v[32:33]
	v_cvt_pk_bf16_f32 v34, v36, v37
	s_mov_b64 s[100:101], 0xc6000
	v_cvt_pk_bf16_f32 v32, v40, v41
	v_cvt_pk_bf16_f32 v33, v42, v43
	v_cvt_pk_bf16_f32 v35, v38, v39
	v_lshl_add_u64 v[36:37], v[250:251], 0, s[100:101]
	flat_store_dwordx4 v[36:37], v[32:35]
	s_nop 1
	v_mul_f32_e32 v32, 0xbfb8aa3b, v28
	v_mul_f32_e32 v33, 0xbfb8aa3b, v29
	v_exp_f32_e32 v32, v32
	v_exp_f32_e32 v33, v33
	v_add_f32_e32 v32, 1.0, v32
	v_add_f32_e32 v33, 1.0, v33
	v_rcp_f32_e32 v32, v32
	v_rcp_f32_e32 v33, v33
	s_nop 0
	v_pk_mul_f32 v[28:29], v[28:29], v[32:33]
	s_nop 0
	v_pk_mul_f32 v[24:25], v[24:25], v[28:29]
	v_pk_mul_f32 v[28:29], v[30:31], v[146:147] op_sel_hi:[1,0]
	s_nop 0
	v_mul_f32_e32 v30, 0xbfb8aa3b, v28
	v_mul_f32_e32 v31, 0xbfb8aa3b, v29
	v_exp_f32_e32 v30, v30
	v_exp_f32_e32 v31, v31
	v_add_f32_e32 v30, 1.0, v30
	v_add_f32_e32 v31, 1.0, v31
	v_rcp_f32_e32 v30, v30
	v_rcp_f32_e32 v31, v31
	s_nop 0
	v_pk_mul_f32 v[28:29], v[28:29], v[30:31]
	s_nop 0
	v_pk_mul_f32 v[26:27], v[26:27], v[28:29]
	v_mul_f32_e32 v28, 0xbfb8aa3b, v20
	v_mul_f32_e32 v29, 0xbfb8aa3b, v21
	v_exp_f32_e32 v28, v28
	v_exp_f32_e32 v29, v29
	v_add_f32_e32 v28, 1.0, v28
	v_add_f32_e32 v29, 1.0, v29
	v_rcp_f32_e32 v28, v28
	v_rcp_f32_e32 v29, v29
	s_nop 0
	v_pk_mul_f32 v[20:21], v[20:21], v[28:29]
	s_nop 0
	v_pk_mul_f32 v[20:21], v[16:17], v[20:21]
	v_pk_mul_f32 v[16:17], v[22:23], v[146:147] op_sel_hi:[1,0]
	v_add_u32_e32 v28, 0xa0, v173
	v_mul_f32_e32 v22, 0xbfb8aa3b, v16
	v_mul_f32_e32 v23, 0xbfb8aa3b, v17
	v_exp_f32_e32 v22, v22
	v_exp_f32_e32 v23, v23
	v_add_f32_e32 v22, 1.0, v22
	v_add_f32_e32 v23, 1.0, v23
	v_rcp_f32_e32 v22, v22
	v_rcp_f32_e32 v23, v23
	s_nop 0
	v_pk_mul_f32 v[16:17], v[16:17], v[22:23]
	s_nop 0
	v_pk_mul_f32 v[22:23], v[18:19], v[16:17]
	v_cvt_pk_bf16_f32 v18, v20, v21
	s_mov_b64 s[100:101], 0xdc000
	v_cvt_pk_bf16_f32 v16, v24, v25
	v_cvt_pk_bf16_f32 v17, v26, v27
	v_cvt_pk_bf16_f32 v19, v22, v23
	v_lshl_add_u64 v[20:21], v[250:251], 0, s[100:101]
	flat_store_dwordx4 v[20:21], v[16:19]
	s_nop 1
	v_mov_b32_e32 v16, v147
	v_pk_mul_f32 v[12:13], v[12:13], v[16:17] op_sel_hi:[1,0]
	s_nop 0
	v_mul_f32_e32 v17, 0xbfb8aa3b, v12
	v_exp_f32_e32 v17, v17
	s_nop 0
	v_add_f32_e32 v17, 1.0, v17
	v_rcp_f32_e32 v18, v17
	v_pk_mul_f32 v[8:9], v[8:9], v[16:17] op_sel_hi:[1,0]
	v_mul_f32_e32 v17, 0xbfb8aa3b, v13
	v_exp_f32_e32 v17, v17
	s_nop 0
	v_add_f32_e32 v17, 1.0, v17
	v_rcp_f32_e32 v19, v17
	v_pk_mul_f32 v[10:11], v[10:11], v[16:17] op_sel_hi:[1,0]
	v_pk_mul_f32 v[4:5], v[4:5], v[16:17] op_sel_hi:[1,0]
	v_pk_mul_f32 v[0:1], v[0:1], v[16:17] op_sel_hi:[1,0]
	v_pk_mul_f32 v[12:13], v[12:13], v[18:19]
	v_pk_mul_f32 v[2:3], v[2:3], v[16:17] op_sel_hi:[1,0]
	v_pk_mul_f32 v[8:9], v[8:9], v[12:13]
	v_pk_mul_f32 v[12:13], v[14:15], v[16:17] op_sel_hi:[1,0]
	s_nop 0
	v_mul_f32_e32 v14, 0xbfb8aa3b, v12
	v_mul_f32_e32 v15, 0xbfb8aa3b, v13
	v_exp_f32_e32 v14, v14
	v_exp_f32_e32 v15, v15
	v_add_f32_e32 v14, 1.0, v14
	v_add_f32_e32 v15, 1.0, v15
	v_rcp_f32_e32 v14, v14
	v_rcp_f32_e32 v15, v15
	s_nop 0
	v_pk_mul_f32 v[12:13], v[12:13], v[14:15]
	s_nop 0
	v_pk_mul_f32 v[10:11], v[10:11], v[12:13]
	v_mul_f32_e32 v12, 0xbfb8aa3b, v4
	v_mul_f32_e32 v13, 0xbfb8aa3b, v5
	v_exp_f32_e32 v12, v12
	v_exp_f32_e32 v13, v13
	v_add_f32_e32 v12, 1.0, v12
	v_add_f32_e32 v13, 1.0, v13
	v_rcp_f32_e32 v12, v12
	v_rcp_f32_e32 v13, v13
	s_nop 0
	v_pk_mul_f32 v[4:5], v[4:5], v[12:13]
	s_nop 0
	v_pk_mul_f32 v[4:5], v[0:1], v[4:5]
	v_pk_mul_f32 v[0:1], v[6:7], v[16:17] op_sel_hi:[1,0]
	v_add_u32_e32 v12, 0xb0, v173
	v_mul_f32_e32 v6, 0xbfb8aa3b, v0
	v_mul_f32_e32 v7, 0xbfb8aa3b, v1
	v_exp_f32_e32 v6, v6
	v_exp_f32_e32 v7, v7
	v_add_f32_e32 v6, 1.0, v6
	v_add_f32_e32 v7, 1.0, v7
	v_rcp_f32_e32 v6, v6
	v_rcp_f32_e32 v7, v7
	s_nop 0
	v_pk_mul_f32 v[0:1], v[0:1], v[6:7]
	s_nop 0
	v_pk_mul_f32 v[6:7], v[2:3], v[0:1]
	v_cvt_pk_bf16_f32 v2, v4, v5
	s_mov_b64 s[100:101], 0xf2000
	v_cvt_pk_bf16_f32 v0, v8, v9
	v_cvt_pk_bf16_f32 v1, v10, v11
	v_cvt_pk_bf16_f32 v3, v6, v7
	v_lshl_add_u64 v[4:5], v[250:251], 0, s[100:101]
	s_mov_b64 s[8:9], -1
	flat_store_dwordx4 v[4:5], v[0:3]
	s_cbranch_vccnz .LBB0_3839
	s_andn2_b64 vcc, exec, s[48:49]
	s_cbranch_vccnz .LBB0_3838
	s_barrier
	s_branch .LBB0_3838
